# v45 + adaLN GEMV k-loop: weight-row loads software-pipelined (each row reloaded for the next k-step right after use, 16 loads always in flight)
# speedup vs baseline: 1.0118x; 1.0012x over previous
; #define ARGP(i) ka_ptr(ka, (i) * 8)
; __global__ void __launch_bounds__(NWAVES * 64, 2) fwd_kernel(Args args_unused) {
;     ...
;                 float a0 = 0.f, a1 = 0.f, a2 = 0.f, a3 = 0.f, a4 = 0.f, a5 = 0.f, a6 = 0.f, a7 = 0.f, a8 = 0.f;
;                 const float* wp = ARGP(I_WMOD) + (size_t)k0 * NMOD + col;
; #pragma unroll 16
;                 for (int kk = 0; kk < 64; ++kk) { const float w = wp[(size_t)kk * NMOD];
;                     a0 += scr[kk] * w; a1 += scr[64 + kk] * w; a2 += scr[128 + kk] * w; a3 += scr[192 + kk] * w; a4 += scr[256 + kk] * w; a5 += scr[320 + kk] * w; a6 += scr[384 + kk] * w; a7 += scr[448 + kk] * w; a8 += scr[512 + kk] * w; }
.LBB0_105:
	s_or_b64 exec, exec, s[14:15]
	s_mulk_i32 s60, 0x60
	s_sub_i32 s12, s90, s60
	s_waitcnt lgkmcnt(0)
	s_waitcnt lgkmcnt(4)
	v_lshl_add_u32 v34, s12, 6, v0
	s_load_dwordx2 s[12:13], s[96:97], 32
	s_waitcnt lgkmcnt(0)
	s_mul_hi_i32 s14, s34, 0x6000
	s_mulk_i32 s34, 0x6000
	s_add_u32 s12, s12, s34
	s_addc_u32 s13, s13, s14
	v_ashrrev_i32_e32 v35, 31, v34
	v_mov_b32_e32 v6, 0
	s_waitcnt lgkmcnt(3)
	v_lshl_add_u64 v[36:37], v[34:35], 2, s[12:13]
	s_mov_b64 s[12:13], 0
	s_mov_b32 s14, s0
	v_mov_b32_e32 v44, 0
	v_mov_b32_e32 v45, v6
	v_mov_b32_e32 v42, 0
	v_mov_b32_e32 v43, v6
	s_waitcnt lgkmcnt(0)
	v_mov_b32_e32 v40, 0
	v_mov_b32_e32 v41, v6
	v_mov_b32_e32 v38, 0
	v_mov_b32_e32 v39, v6
	v_lshl_add_u64 v[46:47], v[36:37], 0, s[12:13]
	v_add_co_u32_e32 v106, vcc, 0x6000, v46
	s_nop 0
	v_addc_co_u32_e32 v107, vcc, 0, v47, vcc
	v_add_co_u32_e32 v212, vcc, 0xc000, v46
	s_nop 0
	v_addc_co_u32_e32 v213, vcc, 0, v47, vcc
	v_add_co_u32_e32 v214, vcc, 0x12000, v46
	s_nop 0
	v_addc_co_u32_e32 v215, vcc, 0, v47, vcc
	v_add_co_u32_e32 v216, vcc, 0x18000, v46
	s_nop 0
	v_addc_co_u32_e32 v217, vcc, 0, v47, vcc
	v_add_co_u32_e32 v218, vcc, 0x1e000, v46
	s_nop 0
	v_addc_co_u32_e32 v219, vcc, 0, v47, vcc
	v_add_co_u32_e32 v220, vcc, 0x24000, v46
	s_nop 0
	v_addc_co_u32_e32 v221, vcc, 0, v47, vcc
	v_add_co_u32_e32 v222, vcc, 0x2a000, v46
	s_nop 0
	v_addc_co_u32_e32 v223, vcc, 0, v47, vcc
	v_add_co_u32_e32 v224, vcc, 0x30000, v46
	s_nop 0
	v_addc_co_u32_e32 v225, vcc, 0, v47, vcc
	v_add_co_u32_e32 v226, vcc, 0x36000, v46
	s_nop 0
	v_addc_co_u32_e32 v227, vcc, 0, v47, vcc
	v_add_co_u32_e32 v228, vcc, 0x3c000, v46
	s_nop 0
	v_addc_co_u32_e32 v229, vcc, 0, v47, vcc
	v_add_co_u32_e32 v230, vcc, 0x42000, v46
	s_nop 0
	v_addc_co_u32_e32 v231, vcc, 0, v47, vcc
	v_add_co_u32_e32 v232, vcc, 0x48000, v46
	s_nop 0
	v_addc_co_u32_e32 v233, vcc, 0, v47, vcc
	v_add_co_u32_e32 v234, vcc, 0x4e000, v46
	s_nop 0
	v_addc_co_u32_e32 v235, vcc, 0, v47, vcc
	v_add_co_u32_e32 v236, vcc, 0x54000, v46
	s_nop 0
	v_addc_co_u32_e32 v237, vcc, 0, v47, vcc
	global_load_dword v48, v[46:47], off nt
	global_load_dword v106, v[106:107], off nt
	global_load_dword v212, v[212:213], off nt
	global_load_dword v214, v[214:215], off nt
	global_load_dword v216, v[216:217], off nt
	global_load_dword v218, v[218:219], off nt
	global_load_dword v220, v[220:221], off nt
	global_load_dword v222, v[222:223], off nt
	global_load_dword v224, v[224:225], off nt
	global_load_dword v226, v[226:227], off nt
	global_load_dword v228, v[228:229], off nt
	global_load_dword v230, v[230:231], off nt
	global_load_dword v232, v[232:233], off nt
	global_load_dword v234, v[234:235], off nt
	global_load_dword v236, v[236:237], off nt
	v_add_co_u32_e32 v46, vcc, 0x5a000, v46
	s_nop 0
	v_addc_co_u32_e32 v47, vcc, 0, v47, vcc
	global_load_dword v46, v[46:47], off nt
.LBB0_106:
	s_cmp_eq_u32 s12, 0x120000
	s_cselect_b32 s20, 0, 0x60000
	v_lshl_add_u64 v[246:247], v[36:37], 0, s[12:13]
	v_add_co_u32_e32 v246, vcc, s20, v246
	s_nop 0
	v_addc_co_u32_e32 v247, vcc, 0, v247, vcc
	s_nop 0
	s_nop 0
	v_mov_b32_e32 v31, s14
	s_nop 0
	ds_read_b128 v[50:53], v31
	ds_read_b128 v[54:57], v31 offset:16
	ds_read_b128 v[58:61], v31 offset:32
	ds_read_b128 v[62:65], v31 offset:48
	ds_read_b128 v[66:69], v31 offset:256
	ds_read_b128 v[70:73], v31 offset:272
	ds_read_b128 v[74:77], v31 offset:512
	ds_read_b128 v[78:81], v31 offset:528
	ds_read_b128 v[82:85], v31 offset:768
	ds_read_b128 v[86:89], v31 offset:784
	ds_read_b128 v[90:93], v31 offset:1024
	ds_read_b128 v[94:97], v31 offset:1040
	ds_read_b128 v[98:101], v31 offset:1280
	ds_read_b128 v[102:105], v31 offset:1296
	ds_read_b128 v[124:127], v31 offset:1536
	ds_read_b128 v[128:131], v31 offset:1552
	ds_read_b128 v[132:135], v31 offset:1792
	ds_read_b128 v[136:139], v31 offset:1808
	ds_read_b128 v[140:143], v31 offset:2048
	ds_read_b128 v[144:147], v31 offset:2064
	ds_read_b128 v[148:151], v31 offset:288
	ds_read_b128 v[152:155], v31 offset:304
	ds_read_b128 v[156:159], v31 offset:544
	ds_read_b128 v[160:163], v31 offset:560
	ds_read_b128 v[164:167], v31 offset:800
	ds_read_b128 v[168:171], v31 offset:816
	ds_read_b128 v[172:175], v31 offset:1056
	ds_read_b128 v[176:179], v31 offset:1072
	ds_read_b128 v[180:183], v31 offset:1312
	ds_read_b128 v[184:187], v31 offset:1328
	ds_read_b128 v[188:191], v31 offset:1568
	ds_read_b128 v[192:195], v31 offset:1584
	ds_read_b128 v[196:199], v31 offset:1824
	ds_read_b128 v[200:203], v31 offset:1840
	ds_read_b128 v[204:207], v31 offset:2080
	ds_read_b128 v[208:211], v31 offset:2096
	s_waitcnt lgkmcnt(14)
	v_mov_b32_e32 v238, v50
	v_mov_b32_e32 v239, v66
	s_nop 0
	v_mov_b32_e32 v240, v74
	s_nop 0
	v_mov_b32_e32 v241, v82
	s_nop 0
	v_mov_b32_e32 v242, v90
	s_nop 0
	v_mov_b32_e32 v243, v98
	s_nop 0
	v_mov_b32_e32 v244, v124
	s_nop 0
	v_mov_b32_e32 v245, v132
	s_nop 0
	v_mov_b32_e32 v66, v51
	s_nop 0
	s_nop 0
	s_nop 0
	s_nop 0
	s_nop 0
	s_nop 0
	s_nop 0
	s_nop 0
	s_nop 0
	s_nop 0
	s_nop 0
	s_nop 0
	s_nop 0
	s_nop 0
	s_nop 0
	v_mov_b32_e32 v82, v75
	v_mov_b32_e32 v98, v91
	v_mov_b32_e32 v132, v125
	v_mov_b32_e32 v50, v52
	v_mov_b32_e32 v51, v68
	v_mov_b32_e32 v74, v76
	v_mov_b32_e32 v75, v84
	v_mov_b32_e32 v90, v92
	v_mov_b32_e32 v91, v100
	v_mov_b32_e32 v124, v126
	v_mov_b32_e32 v125, v134
	s_waitcnt vmcnt(15)
; __global__ void __launch_bounds__(NWAVES * 64, 2) fwd_kernel(Args args_unused) {
;     ...
;                 for (int kk = 0; kk < 64; ++kk) { const float w = wp[(size_t)kk * NMOD];
;                     a0 += scr[kk] * w; a1 += scr[64 + kk] * w; a2 += scr[128 + kk] * w; a3 += scr[192 + kk] * w; a4 += scr[256 + kk] * w; a5 += scr[320 + kk] * w; a6 += scr[384 + kk] * w; a7 += scr[448 + kk] * w; a8 += scr[512 + kk] * w; }
	v_pk_fma_f32 v[44:45], v[48:49], v[238:239], v[44:45] op_sel_hi:[0,1,1]
	v_pk_fma_f32 v[42:43], v[48:49], v[240:241], v[42:43] op_sel_hi:[0,1,1]
	v_pk_fma_f32 v[40:41], v[48:49], v[242:243], v[40:41] op_sel_hi:[0,1,1]
	v_pk_fma_f32 v[38:39], v[48:49], v[244:245], v[38:39] op_sel_hi:[0,1,1]
	v_fmac_f32_e32 v6, v48, v140
	global_load_dword v48, v[246:247], off nt
	v_mov_b32_e32 v68, v53
	v_mov_b32_e32 v84, v77
	v_mov_b32_e32 v100, v93
	v_mov_b32_e32 v134, v127
	v_mov_b32_e32 v52, v54
	v_mov_b32_e32 v53, v70
	v_mov_b32_e32 v76, v78
	v_mov_b32_e32 v77, v86
	v_mov_b32_e32 v92, v94
	v_mov_b32_e32 v93, v102
	v_mov_b32_e32 v126, v128
	v_mov_b32_e32 v127, v136
	v_mov_b32_e32 v70, v55
	v_mov_b32_e32 v86, v79
	v_mov_b32_e32 v102, v95
	v_mov_b32_e32 v136, v129
	v_mov_b32_e32 v54, v56
	v_mov_b32_e32 v55, v72
	v_mov_b32_e32 v78, v80
	v_mov_b32_e32 v79, v88
	v_mov_b32_e32 v94, v96
	v_mov_b32_e32 v95, v104
	v_mov_b32_e32 v128, v130
	v_mov_b32_e32 v129, v138
	v_mov_b32_e32 v72, v57
	v_mov_b32_e32 v88, v81
	v_mov_b32_e32 v104, v97
	v_mov_b32_e32 v138, v131
	v_mov_b32_e32 v56, v58
	v_mov_b32_e32 v57, v148
	s_waitcnt lgkmcnt(13)
	v_mov_b32_e32 v80, v156
	s_waitcnt lgkmcnt(11)
	v_mov_b32_e32 v81, v164
	s_waitcnt lgkmcnt(9)
	v_mov_b32_e32 v96, v172
	s_waitcnt lgkmcnt(7)
	v_mov_b32_e32 v97, v180
	s_waitcnt lgkmcnt(5)
	v_mov_b32_e32 v130, v188
	s_waitcnt lgkmcnt(3)
	v_mov_b32_e32 v131, v196
	v_mov_b32_e32 v148, v59
	v_mov_b32_e32 v164, v157
	v_mov_b32_e32 v180, v173
	v_mov_b32_e32 v196, v189
	v_mov_b32_e32 v58, v60
	v_mov_b32_e32 v59, v150
	v_mov_b32_e32 v156, v158
	v_mov_b32_e32 v157, v166
	v_mov_b32_e32 v172, v174
	v_mov_b32_e32 v173, v182
	v_mov_b32_e32 v188, v190
	v_mov_b32_e32 v189, v198
	v_mov_b32_e32 v150, v61
	s_waitcnt vmcnt(15)
	v_pk_fma_f32 v[44:45], v[106:107], v[66:67], v[44:45] op_sel_hi:[0,1,1]
	v_pk_fma_f32 v[42:43], v[106:107], v[82:83], v[42:43] op_sel_hi:[0,1,1]
	v_pk_fma_f32 v[40:41], v[106:107], v[98:99], v[40:41] op_sel_hi:[0,1,1]
	v_pk_fma_f32 v[38:39], v[106:107], v[132:133], v[38:39] op_sel_hi:[0,1,1]
	v_fmac_f32_e32 v6, v106, v141
	v_add_co_u32_e32 v106, vcc, 0x6000, v246
	s_nop 0
	v_addc_co_u32_e32 v107, vcc, 0, v247, vcc
	global_load_dword v106, v[106:107], off nt
	s_waitcnt vmcnt(15)
	v_pk_fma_f32 v[44:45], v[212:213], v[50:51], v[44:45] op_sel_hi:[0,1,1]
	v_pk_fma_f32 v[42:43], v[212:213], v[74:75], v[42:43] op_sel_hi:[0,1,1]
	v_pk_fma_f32 v[40:41], v[212:213], v[90:91], v[40:41] op_sel_hi:[0,1,1]
	v_pk_fma_f32 v[38:39], v[212:213], v[124:125], v[38:39] op_sel_hi:[0,1,1]
	v_fmac_f32_e32 v6, v212, v142
	v_add_co_u32_e32 v212, vcc, 0xc000, v246
	s_nop 0
	v_addc_co_u32_e32 v213, vcc, 0, v247, vcc
	global_load_dword v212, v[212:213], off nt
	s_waitcnt vmcnt(15)
	v_pk_fma_f32 v[44:45], v[214:215], v[68:69], v[44:45] op_sel_hi:[0,1,1]
	v_pk_fma_f32 v[42:43], v[214:215], v[84:85], v[42:43] op_sel_hi:[0,1,1]
	v_pk_fma_f32 v[40:41], v[214:215], v[100:101], v[40:41] op_sel_hi:[0,1,1]
	v_pk_fma_f32 v[38:39], v[214:215], v[134:135], v[38:39] op_sel_hi:[0,1,1]
	v_fmac_f32_e32 v6, v214, v143
	v_add_co_u32_e32 v214, vcc, 0x12000, v246
	s_nop 0
	v_addc_co_u32_e32 v215, vcc, 0, v247, vcc
	global_load_dword v214, v[214:215], off nt
	s_waitcnt vmcnt(15)
	v_pk_fma_f32 v[44:45], v[216:217], v[52:53], v[44:45] op_sel_hi:[0,1,1]
	v_pk_fma_f32 v[42:43], v[216:217], v[76:77], v[42:43] op_sel_hi:[0,1,1]
	v_pk_fma_f32 v[40:41], v[216:217], v[92:93], v[40:41] op_sel_hi:[0,1,1]
	v_pk_fma_f32 v[38:39], v[216:217], v[126:127], v[38:39] op_sel_hi:[0,1,1]
	v_fmac_f32_e32 v6, v216, v144
	v_add_co_u32_e32 v216, vcc, 0x18000, v246
	s_nop 0
	v_addc_co_u32_e32 v217, vcc, 0, v247, vcc
	global_load_dword v216, v[216:217], off nt
	s_waitcnt vmcnt(15)
	v_pk_fma_f32 v[44:45], v[218:219], v[70:71], v[44:45] op_sel_hi:[0,1,1]
	v_pk_fma_f32 v[42:43], v[218:219], v[86:87], v[42:43] op_sel_hi:[0,1,1]
	v_pk_fma_f32 v[40:41], v[218:219], v[102:103], v[40:41] op_sel_hi:[0,1,1]
	v_pk_fma_f32 v[38:39], v[218:219], v[136:137], v[38:39] op_sel_hi:[0,1,1]
	v_fmac_f32_e32 v6, v218, v145
	v_add_co_u32_e32 v218, vcc, 0x1e000, v246
	s_nop 0
	v_addc_co_u32_e32 v219, vcc, 0, v247, vcc
	global_load_dword v218, v[218:219], off nt
	s_waitcnt vmcnt(15)
	v_pk_fma_f32 v[44:45], v[220:221], v[54:55], v[44:45] op_sel_hi:[0,1,1]
	v_pk_fma_f32 v[42:43], v[220:221], v[78:79], v[42:43] op_sel_hi:[0,1,1]
	v_pk_fma_f32 v[40:41], v[220:221], v[94:95], v[40:41] op_sel_hi:[0,1,1]
	v_pk_fma_f32 v[38:39], v[220:221], v[128:129], v[38:39] op_sel_hi:[0,1,1]
	v_fmac_f32_e32 v6, v220, v146
	v_add_co_u32_e32 v220, vcc, 0x24000, v246
	s_nop 0
	v_addc_co_u32_e32 v221, vcc, 0, v247, vcc
	global_load_dword v220, v[220:221], off nt
	s_waitcnt vmcnt(15)
	v_pk_fma_f32 v[44:45], v[222:223], v[72:73], v[44:45] op_sel_hi:[0,1,1]
	v_pk_fma_f32 v[42:43], v[222:223], v[88:89], v[42:43] op_sel_hi:[0,1,1]
	v_pk_fma_f32 v[40:41], v[222:223], v[104:105], v[40:41] op_sel_hi:[0,1,1]
	v_pk_fma_f32 v[38:39], v[222:223], v[138:139], v[38:39] op_sel_hi:[0,1,1]
	v_fmac_f32_e32 v6, v222, v147
	v_add_co_u32_e32 v222, vcc, 0x2a000, v246
	s_nop 0
	v_addc_co_u32_e32 v223, vcc, 0, v247, vcc
	global_load_dword v222, v[222:223], off nt
	s_waitcnt vmcnt(15)
; #define ARGP(i) ka_ptr(ka, (i) * 8)
; __global__ void __launch_bounds__(NWAVES * 64, 2) fwd_kernel(Args args_unused) {
;     ...
;                 for (int kk = 0; kk < 64; ++kk) { const float w = wp[(size_t)kk * NMOD];
;                     a0 += scr[kk] * w; a1 += scr[64 + kk] * w; a2 += scr[128 + kk] * w; a3 += scr[192 + kk] * w; a4 += scr[256 + kk] * w; a5 += scr[320 + kk] * w; a6 += scr[384 + kk] * w; a7 += scr[448 + kk] * w; a8 += scr[512 + kk] * w; }
;                 const float bm = (kc == 0) ? ARGP(I_BMOD)[col] : 0.f;
	v_pk_fma_f32 v[44:45], v[224:225], v[56:57], v[44:45] op_sel_hi:[0,1,1]
	v_pk_fma_f32 v[42:43], v[224:225], v[80:81], v[42:43] op_sel_hi:[0,1,1]
	v_pk_fma_f32 v[40:41], v[224:225], v[96:97], v[40:41] op_sel_hi:[0,1,1]
	v_pk_fma_f32 v[38:39], v[224:225], v[130:131], v[38:39] op_sel_hi:[0,1,1]
	s_waitcnt lgkmcnt(1)
	v_fmac_f32_e32 v6, v224, v204
	v_add_co_u32_e32 v224, vcc, 0x30000, v246
	s_nop 0
	v_addc_co_u32_e32 v225, vcc, 0, v247, vcc
	global_load_dword v224, v[224:225], off nt
	s_waitcnt vmcnt(15)
	v_pk_fma_f32 v[44:45], v[226:227], v[148:149], v[44:45] op_sel_hi:[0,1,1]
	v_pk_fma_f32 v[42:43], v[226:227], v[164:165], v[42:43] op_sel_hi:[0,1,1]
	v_pk_fma_f32 v[40:41], v[226:227], v[180:181], v[40:41] op_sel_hi:[0,1,1]
	v_pk_fma_f32 v[38:39], v[226:227], v[196:197], v[38:39] op_sel_hi:[0,1,1]
	v_fmac_f32_e32 v6, v226, v205
	v_add_co_u32_e32 v226, vcc, 0x36000, v246
	s_nop 0
	v_addc_co_u32_e32 v227, vcc, 0, v247, vcc
	global_load_dword v226, v[226:227], off nt
	v_mov_b32_e32 v166, v159
	v_mov_b32_e32 v182, v175
	v_mov_b32_e32 v198, v191
	s_waitcnt vmcnt(15)
	v_pk_fma_f32 v[44:45], v[228:229], v[58:59], v[44:45] op_sel_hi:[0,1,1]
	v_pk_fma_f32 v[42:43], v[228:229], v[156:157], v[42:43] op_sel_hi:[0,1,1]
	v_pk_fma_f32 v[40:41], v[228:229], v[172:173], v[40:41] op_sel_hi:[0,1,1]
	v_pk_fma_f32 v[38:39], v[228:229], v[188:189], v[38:39] op_sel_hi:[0,1,1]
	v_fmac_f32_e32 v6, v228, v206
	v_add_co_u32_e32 v228, vcc, 0x3c000, v246
	s_nop 0
	v_addc_co_u32_e32 v229, vcc, 0, v247, vcc
	global_load_dword v228, v[228:229], off nt
	v_mov_b32_e32 v60, v62
	v_mov_b32_e32 v61, v152
	v_mov_b32_e32 v158, v160
	v_mov_b32_e32 v159, v168
	v_mov_b32_e32 v174, v176
	v_mov_b32_e32 v175, v184
	v_mov_b32_e32 v190, v192
	v_mov_b32_e32 v191, v200
	s_waitcnt vmcnt(15)
	v_pk_fma_f32 v[44:45], v[230:231], v[150:151], v[44:45] op_sel_hi:[0,1,1]
	v_pk_fma_f32 v[42:43], v[230:231], v[166:167], v[42:43] op_sel_hi:[0,1,1]
	v_pk_fma_f32 v[40:41], v[230:231], v[182:183], v[40:41] op_sel_hi:[0,1,1]
	v_pk_fma_f32 v[38:39], v[230:231], v[198:199], v[38:39] op_sel_hi:[0,1,1]
	v_fmac_f32_e32 v6, v230, v207
	v_add_co_u32_e32 v230, vcc, 0x42000, v246
	s_nop 0
	v_addc_co_u32_e32 v231, vcc, 0, v247, vcc
	global_load_dword v230, v[230:231], off nt
	v_mov_b32_e32 v152, v63
	v_mov_b32_e32 v168, v161
	v_mov_b32_e32 v184, v177
	v_mov_b32_e32 v200, v193
	s_waitcnt vmcnt(15)
	v_pk_fma_f32 v[44:45], v[232:233], v[60:61], v[44:45] op_sel_hi:[0,1,1]
	v_pk_fma_f32 v[42:43], v[232:233], v[158:159], v[42:43] op_sel_hi:[0,1,1]
	v_pk_fma_f32 v[40:41], v[232:233], v[174:175], v[40:41] op_sel_hi:[0,1,1]
	v_pk_fma_f32 v[38:39], v[232:233], v[190:191], v[38:39] op_sel_hi:[0,1,1]
	s_waitcnt lgkmcnt(0)
	v_fmac_f32_e32 v6, v232, v208
	v_add_co_u32_e32 v232, vcc, 0x48000, v246
	s_nop 0
	v_addc_co_u32_e32 v233, vcc, 0, v247, vcc
	global_load_dword v232, v[232:233], off nt
	s_add_u32 s12, s12, 0x60000
	v_mov_b32_e32 v62, v64
	v_mov_b32_e32 v63, v154
	v_mov_b32_e32 v160, v162
	v_mov_b32_e32 v161, v170
	v_mov_b32_e32 v176, v178
	v_mov_b32_e32 v177, v186
	v_mov_b32_e32 v192, v194
	v_mov_b32_e32 v193, v202
	s_waitcnt vmcnt(15)
	v_pk_fma_f32 v[44:45], v[234:235], v[152:153], v[44:45] op_sel_hi:[0,1,1]
	v_pk_fma_f32 v[42:43], v[234:235], v[168:169], v[42:43] op_sel_hi:[0,1,1]
	v_pk_fma_f32 v[40:41], v[234:235], v[184:185], v[40:41] op_sel_hi:[0,1,1]
	v_pk_fma_f32 v[38:39], v[234:235], v[200:201], v[38:39] op_sel_hi:[0,1,1]
	v_fmac_f32_e32 v6, v234, v209
	v_add_co_u32_e32 v234, vcc, 0x4e000, v246
	s_nop 0
	v_addc_co_u32_e32 v235, vcc, 0, v247, vcc
	global_load_dword v234, v[234:235], off nt
	s_addc_u32 s13, s13, 0
	s_add_i32 s14, s14, 64
	v_mov_b32_e32 v154, v65
	v_mov_b32_e32 v170, v163
	v_mov_b32_e32 v186, v179
	v_mov_b32_e32 v202, v195
	s_waitcnt vmcnt(15)
	v_pk_fma_f32 v[44:45], v[236:237], v[62:63], v[44:45] op_sel_hi:[0,1,1]
	v_pk_fma_f32 v[42:43], v[236:237], v[160:161], v[42:43] op_sel_hi:[0,1,1]
	v_pk_fma_f32 v[40:41], v[236:237], v[176:177], v[40:41] op_sel_hi:[0,1,1]
	v_pk_fma_f32 v[38:39], v[236:237], v[192:193], v[38:39] op_sel_hi:[0,1,1]
	v_fmac_f32_e32 v6, v236, v210
	v_add_co_u32_e32 v236, vcc, 0x54000, v246
	s_nop 0
	v_addc_co_u32_e32 v237, vcc, 0, v247, vcc
	global_load_dword v236, v[236:237], off nt
	s_cmp_eq_u32 s12, 0x180000
	s_waitcnt vmcnt(15)
	v_pk_fma_f32 v[44:45], v[46:47], v[154:155], v[44:45] op_sel_hi:[0,1,1]
	v_pk_fma_f32 v[42:43], v[46:47], v[170:171], v[42:43] op_sel_hi:[0,1,1]
	v_pk_fma_f32 v[40:41], v[46:47], v[186:187], v[40:41] op_sel_hi:[0,1,1]
	v_pk_fma_f32 v[38:39], v[46:47], v[202:203], v[38:39] op_sel_hi:[0,1,1]
	v_fmac_f32_e32 v6, v46, v211
	v_add_co_u32_e32 v46, vcc, 0x5a000, v246
	s_nop 0
	v_addc_co_u32_e32 v47, vcc, 0, v247, vcc
	global_load_dword v46, v[46:47], off nt
	s_cbranch_scc0 .LBB0_106
	s_add_i32 s12, s90, 0x5f
	s_cmpk_lt_u32 s12, 0xbf
	v_mov_b32_e32 v31, 0
	s_cbranch_scc0 .LBB0_23
	s_load_dwordx2 s[12:13], s[96:97], 40
	s_waitcnt lgkmcnt(0)
	s_nop 0
	v_lshl_add_u64 v[36:37], v[34:35], 2, s[12:13]
	global_load_dword v31, v[36:37], off nt
	s_branch .LBB0_23
